# alternate k0/k1 order in successive same-accumulator MFMA pairs so consecutive MFMAs across pairs share one operand
# baseline (speedup 1.0000x reference)
.LBB0_169:
	s_add_u32 s34, s50, 0xfff80080
	s_addc_u32 s35, s51, -1
	s_add_i32 s52, 0, 0x10000
	s_cmp_eq_u32 s77, 28
	s_cselect_b32 s55, s36, s35
	s_cselect_b32 s54, s37, s34
	v_add_u32_e32 v145, s52, v142
	s_cselect_b32 s35, s41, s76
	s_cselect_b32 s34, s43, s71
	s_add_i32 s53, 0, 0x14000
	ds_read_b128 v[146:149], v145
	ds_read_b128 v[150:153], v145 offset:1024
	ds_read_b128 v[172:175], v145 offset:2048
	ds_read_b128 v[176:179], v145 offset:3072
	v_add_u32_e32 v145, s53, v142
	ds_read_b128 v[180:183], v145
	ds_read_b128 v[184:187], v145 offset:1024
	ds_read_b128 v[188:191], v145 offset:2048
	ds_read_b128 v[192:195], v145 offset:3072
	v_lshl_add_u64 v[154:155], s[50:51], 0, v[138:139]
	s_add_i32 m0, s57, 0xc000
	ds_read_b128 v[196:199], v144
	ds_read_b128 v[200:203], v144 offset:1024
	ds_read_b128 v[204:207], v144 offset:2048
	ds_read_b128 v[208:211], v144 offset:3072
	ds_read_b128 v[212:215], v144 offset:4096
	ds_read_b128 v[216:219], v144 offset:5120
	ds_read_b128 v[228:231], v144 offset:6144
	ds_read_b128 v[232:235], v144 offset:7168
	global_load_lds_dwordx4 v[154:155], off
	v_lshl_add_u64 v[154:155], s[50:51], 0, v[140:141]
	s_add_i32 m0, s57, 0xe000
	s_nop 0
	global_load_lds_dwordx4 v[154:155], off
	s_waitcnt vmcnt(8)
	s_waitcnt lgkmcnt(0)
	s_barrier
	s_setprio 1
	v_mfma_f32_16x16x32_bf16 v[128:131], v[146:149], v[196:199], v[128:131]
	v_mfma_f32_16x16x32_bf16 v[128:131], v[150:153], v[200:203], v[128:131]
	v_mfma_f32_16x16x32_bf16 v[124:127], v[176:179], v[200:203], v[124:127]
	v_mfma_f32_16x16x32_bf16 v[124:127], v[172:175], v[196:199], v[124:127]
	v_mfma_f32_16x16x32_bf16 v[108:111], v[172:175], v[204:207], v[108:111]
	v_mfma_f32_16x16x32_bf16 v[108:111], v[176:179], v[208:211], v[108:111]
	v_mfma_f32_16x16x32_bf16 v[112:115], v[150:153], v[208:211], v[112:115]
	v_mfma_f32_16x16x32_bf16 v[112:115], v[146:149], v[204:207], v[112:115]
	v_mfma_f32_16x16x32_bf16 v[96:99], v[146:149], v[212:215], v[96:99]
	v_mfma_f32_16x16x32_bf16 v[96:99], v[150:153], v[216:219], v[96:99]
	v_mfma_f32_16x16x32_bf16 v[92:95], v[176:179], v[216:219], v[92:95]
	v_mfma_f32_16x16x32_bf16 v[92:95], v[172:175], v[212:215], v[92:95]
	v_mfma_f32_16x16x32_bf16 v[76:79], v[172:175], v[228:231], v[76:79]
	v_mfma_f32_16x16x32_bf16 v[76:79], v[176:179], v[232:235], v[76:79]
	v_mfma_f32_16x16x32_bf16 v[80:83], v[150:153], v[232:235], v[80:83]
	v_mfma_f32_16x16x32_bf16 v[80:83], v[146:149], v[228:231], v[80:83]
	v_mfma_f32_16x16x32_bf16 v[120:123], v[180:183], v[196:199], v[120:123]
	v_mfma_f32_16x16x32_bf16 v[120:123], v[184:187], v[200:203], v[120:123]
	v_mfma_f32_16x16x32_bf16 v[116:119], v[192:195], v[200:203], v[116:119]
	v_mfma_f32_16x16x32_bf16 v[116:119], v[188:191], v[196:199], v[116:119]
	v_mfma_f32_16x16x32_bf16 v[100:103], v[188:191], v[204:207], v[100:103]
	v_mfma_f32_16x16x32_bf16 v[100:103], v[192:195], v[208:211], v[100:103]
	v_mfma_f32_16x16x32_bf16 v[104:107], v[184:187], v[208:211], v[104:107]
	v_mfma_f32_16x16x32_bf16 v[104:107], v[180:183], v[204:207], v[104:107]
	v_mfma_f32_16x16x32_bf16 v[88:91], v[180:183], v[212:215], v[88:91]
	v_mfma_f32_16x16x32_bf16 v[88:91], v[184:187], v[216:219], v[88:91]
	v_mfma_f32_16x16x32_bf16 v[84:87], v[192:195], v[216:219], v[84:87]
	v_mfma_f32_16x16x32_bf16 v[84:87], v[188:191], v[212:215], v[84:87]
	v_mfma_f32_16x16x32_bf16 v[68:71], v[188:191], v[228:231], v[68:71]
	v_mfma_f32_16x16x32_bf16 v[68:71], v[192:195], v[232:235], v[68:71]
	v_mfma_f32_16x16x32_bf16 v[72:75], v[184:187], v[232:235], v[72:75]
	v_mfma_f32_16x16x32_bf16 v[72:75], v[180:183], v[228:231], v[72:75]
	s_setprio 0
	s_barrier
	s_add_i32 s52, s52, s19
	v_lshl_add_u64 v[154:155], s[34:35], 0, v[134:135]
	s_mov_b32 m0, s52
	ds_read_b128 v[196:199], v144 offset:16384
	ds_read_b128 v[200:203], v144 offset:17408
	ds_read_b128 v[204:207], v144 offset:18432
	ds_read_b128 v[208:211], v144 offset:19456
	ds_read_b128 v[212:215], v144 offset:20480
	ds_read_b128 v[216:219], v144 offset:21504
	ds_read_b128 v[228:231], v144 offset:22528
	ds_read_b128 v[232:235], v144 offset:23552
	global_load_lds_dwordx4 v[154:155], off
	s_add_i32 m0, s52, 0x2000
	s_add_u32 s96, s34, 0x4000
	v_lshl_add_u64 v[154:155], s[34:35], 0, v[0:1]
	s_addc_u32 s97, s35, 0
	s_add_i32 s52, s53, s19
	global_load_lds_dwordx4 v[154:155], off
	v_lshl_add_u64 v[154:155], s[96:97], 0, v[134:135]
	s_mov_b32 m0, s52
	v_lshl_add_u64 v[236:237], s[54:55], 0, v[132:133]
	global_load_lds_dwordx4 v[154:155], off
	v_lshl_add_u64 v[154:155], s[96:97], 0, v[0:1]
	s_add_i32 m0, s52, 0x2000
	s_nop 0
	global_load_lds_dwordx4 v[154:155], off
	v_lshl_add_u64 v[154:155], s[54:55], 0, v[136:137]
	s_mov_b32 m0, s57
	s_nop 0
	global_load_lds_dwordx4 v[154:155], off
	s_mov_b32 m0, s58
	s_nop 0
	global_load_lds_dwordx4 v[236:237], off
	s_waitcnt vmcnt(8)
	s_waitcnt lgkmcnt(0)
	s_barrier
	s_setprio 1
	v_mfma_f32_16x16x32_bf16 v[64:67], v[146:149], v[196:199], v[64:67]
	v_mfma_f32_16x16x32_bf16 v[64:67], v[150:153], v[200:203], v[64:67]
	v_mfma_f32_16x16x32_bf16 v[60:63], v[176:179], v[200:203], v[60:63]
	v_mfma_f32_16x16x32_bf16 v[60:63], v[172:175], v[196:199], v[60:63]
	v_mfma_f32_16x16x32_bf16 v[44:47], v[172:175], v[204:207], v[44:47]
	v_mfma_f32_16x16x32_bf16 v[44:47], v[176:179], v[208:211], v[44:47]
	v_mfma_f32_16x16x32_bf16 v[48:51], v[150:153], v[208:211], v[48:51]
	v_mfma_f32_16x16x32_bf16 v[48:51], v[146:149], v[204:207], v[48:51]
	v_mfma_f32_16x16x32_bf16 v[32:35], v[146:149], v[212:215], v[32:35]
	v_mfma_f32_16x16x32_bf16 v[32:35], v[150:153], v[216:219], v[32:35]
	v_mfma_f32_16x16x32_bf16 v[28:31], v[176:179], v[216:219], v[28:31]
	v_mfma_f32_16x16x32_bf16 v[28:31], v[172:175], v[212:215], v[28:31]
	v_mfma_f32_16x16x32_bf16 v[12:15], v[172:175], v[228:231], v[12:15]
	v_mfma_f32_16x16x32_bf16 v[12:15], v[176:179], v[232:235], v[12:15]
	v_mfma_f32_16x16x32_bf16 v[16:19], v[150:153], v[232:235], v[16:19]
	v_mfma_f32_16x16x32_bf16 v[16:19], v[146:149], v[228:231], v[16:19]
	v_mfma_f32_16x16x32_bf16 v[56:59], v[180:183], v[196:199], v[56:59]
	v_mfma_f32_16x16x32_bf16 v[56:59], v[184:187], v[200:203], v[56:59]
	v_mfma_f32_16x16x32_bf16 v[52:55], v[192:195], v[200:203], v[52:55]
	v_mfma_f32_16x16x32_bf16 v[52:55], v[188:191], v[196:199], v[52:55]
	v_mfma_f32_16x16x32_bf16 v[36:39], v[188:191], v[204:207], v[36:39]
	v_mfma_f32_16x16x32_bf16 v[36:39], v[192:195], v[208:211], v[36:39]
	v_mfma_f32_16x16x32_bf16 v[40:43], v[184:187], v[208:211], v[40:43]
	v_mfma_f32_16x16x32_bf16 v[40:43], v[180:183], v[204:207], v[40:43]
	v_mfma_f32_16x16x32_bf16 v[24:27], v[180:183], v[212:215], v[24:27]
	v_mfma_f32_16x16x32_bf16 v[24:27], v[184:187], v[216:219], v[24:27]
	v_mfma_f32_16x16x32_bf16 v[20:23], v[192:195], v[216:219], v[20:23]
	v_mfma_f32_16x16x32_bf16 v[20:23], v[188:191], v[212:215], v[20:23]
	v_mfma_f32_16x16x32_bf16 v[4:7], v[188:191], v[228:231], v[4:7]
	v_mfma_f32_16x16x32_bf16 v[4:7], v[192:195], v[232:235], v[4:7]
	v_mfma_f32_16x16x32_bf16 v[8:11], v[184:187], v[232:235], v[8:11]
	v_mfma_f32_16x16x32_bf16 v[8:11], v[180:183], v[228:231], v[8:11]
	s_setprio 0
	s_barrier
	s_add_i32 s52, 0, 0x18000
	v_add_u32_e32 v145, s52, v142
	s_add_i32 s53, 0, 0x1c000
	ds_read_b128 v[146:149], v145
	ds_read_b128 v[150:153], v145 offset:1024
	ds_read_b128 v[172:175], v145 offset:2048
	ds_read_b128 v[176:179], v145 offset:3072
	v_add_u32_e32 v145, s53, v142
	ds_read_b128 v[180:183], v145
	ds_read_b128 v[184:187], v145 offset:1024
	ds_read_b128 v[188:191], v145 offset:2048
	ds_read_b128 v[192:195], v145 offset:3072
	s_add_u32 s54, s54, 0x80000
	s_addc_u32 s55, s55, 0
	s_mov_b32 m0, s59
	v_lshl_add_u64 v[238:239], s[54:55], 0, v[136:137]
	ds_read_b128 v[196:199], v144 offset:32768
	ds_read_b128 v[200:203], v144 offset:33792
	ds_read_b128 v[204:207], v144 offset:34816
	ds_read_b128 v[208:211], v144 offset:35840
	ds_read_b128 v[212:215], v144 offset:36864
	ds_read_b128 v[216:219], v144 offset:37888
	ds_read_b128 v[228:231], v144 offset:38912
	ds_read_b128 v[232:235], v144 offset:39936
	global_load_lds_dwordx4 v[238:239], off
	v_lshl_add_u64 v[238:239], s[54:55], 0, v[132:133]
	s_mov_b32 m0, s60
	s_nop 0
	global_load_lds_dwordx4 v[238:239], off
	s_waitcnt vmcnt(8)
	s_waitcnt lgkmcnt(0)
	s_barrier
	s_setprio 1
	v_mfma_f32_16x16x32_bf16 v[128:131], v[146:149], v[196:199], v[128:131]
	v_mfma_f32_16x16x32_bf16 v[128:131], v[150:153], v[200:203], v[128:131]
	v_mfma_f32_16x16x32_bf16 v[124:127], v[176:179], v[200:203], v[124:127]
	v_mfma_f32_16x16x32_bf16 v[124:127], v[172:175], v[196:199], v[124:127]
	v_mfma_f32_16x16x32_bf16 v[108:111], v[172:175], v[204:207], v[108:111]
	v_mfma_f32_16x16x32_bf16 v[108:111], v[176:179], v[208:211], v[108:111]
	v_mfma_f32_16x16x32_bf16 v[112:115], v[150:153], v[208:211], v[112:115]
	v_mfma_f32_16x16x32_bf16 v[112:115], v[146:149], v[204:207], v[112:115]
	v_mfma_f32_16x16x32_bf16 v[96:99], v[146:149], v[212:215], v[96:99]
	v_mfma_f32_16x16x32_bf16 v[96:99], v[150:153], v[216:219], v[96:99]
	v_mfma_f32_16x16x32_bf16 v[92:95], v[176:179], v[216:219], v[92:95]
	v_mfma_f32_16x16x32_bf16 v[92:95], v[172:175], v[212:215], v[92:95]
	v_mfma_f32_16x16x32_bf16 v[76:79], v[172:175], v[228:231], v[76:79]
	v_mfma_f32_16x16x32_bf16 v[76:79], v[176:179], v[232:235], v[76:79]
	v_mfma_f32_16x16x32_bf16 v[80:83], v[150:153], v[232:235], v[80:83]
	v_mfma_f32_16x16x32_bf16 v[80:83], v[146:149], v[228:231], v[80:83]
	v_mfma_f32_16x16x32_bf16 v[120:123], v[180:183], v[196:199], v[120:123]
	v_mfma_f32_16x16x32_bf16 v[120:123], v[184:187], v[200:203], v[120:123]
	v_mfma_f32_16x16x32_bf16 v[116:119], v[192:195], v[200:203], v[116:119]
	v_mfma_f32_16x16x32_bf16 v[116:119], v[188:191], v[196:199], v[116:119]
	v_mfma_f32_16x16x32_bf16 v[100:103], v[188:191], v[204:207], v[100:103]
	v_mfma_f32_16x16x32_bf16 v[100:103], v[192:195], v[208:211], v[100:103]
	v_mfma_f32_16x16x32_bf16 v[104:107], v[184:187], v[208:211], v[104:107]
	v_mfma_f32_16x16x32_bf16 v[104:107], v[180:183], v[204:207], v[104:107]
	v_mfma_f32_16x16x32_bf16 v[88:91], v[180:183], v[212:215], v[88:91]
	v_mfma_f32_16x16x32_bf16 v[88:91], v[184:187], v[216:219], v[88:91]
	v_mfma_f32_16x16x32_bf16 v[84:87], v[192:195], v[216:219], v[84:87]
	v_mfma_f32_16x16x32_bf16 v[84:87], v[188:191], v[212:215], v[84:87]
	v_mfma_f32_16x16x32_bf16 v[68:71], v[188:191], v[228:231], v[68:71]
	v_mfma_f32_16x16x32_bf16 v[68:71], v[192:195], v[232:235], v[68:71]
	v_mfma_f32_16x16x32_bf16 v[72:75], v[184:187], v[232:235], v[72:75]
	v_mfma_f32_16x16x32_bf16 v[72:75], v[180:183], v[228:231], v[72:75]
	s_setprio 0
	s_barrier
	s_add_u32 s54, s34, 0x160000
	s_addc_u32 s55, s35, 0
	s_add_i32 s52, s52, s19
	v_lshl_add_u64 v[238:239], s[54:55], 0, v[134:135]
	s_mov_b32 m0, s52
	ds_read_b128 v[196:199], v144 offset:49152
	ds_read_b128 v[200:203], v144 offset:50176
	ds_read_b128 v[204:207], v144 offset:51200
	ds_read_b128 v[208:211], v144 offset:52224
	ds_read_b128 v[212:215], v144 offset:53248
	ds_read_b128 v[216:219], v144 offset:54272
	ds_read_b128 v[228:231], v144 offset:55296
	ds_read_b128 v[232:235], v144 offset:56320
	global_load_lds_dwordx4 v[238:239], off
	s_add_i32 m0, s52, 0x2000
	s_add_u32 s34, s34, 0x164000
	v_lshl_add_u64 v[238:239], s[54:55], 0, v[0:1]
	s_addc_u32 s35, s35, 0
	s_add_i32 s52, s53, s19
	global_load_lds_dwordx4 v[238:239], off
	v_lshl_add_u64 v[238:239], s[34:35], 0, v[134:135]
	s_mov_b32 m0, s52
	v_lshl_add_u64 v[154:155], v[154:155], 0, s[14:15]
	global_load_lds_dwordx4 v[238:239], off
	v_lshl_add_u64 v[238:239], s[34:35], 0, v[0:1]
	s_add_i32 m0, s52, 0x2000
	s_nop 0
	global_load_lds_dwordx4 v[238:239], off
	s_mov_b32 m0, s61
	s_nop 0
	global_load_lds_dwordx4 v[154:155], off
	v_lshl_add_u64 v[154:155], v[236:237], 0, s[14:15]
	s_mov_b32 m0, s62
	s_nop 0
	global_load_lds_dwordx4 v[154:155], off
	s_waitcnt vmcnt(8)
	s_waitcnt lgkmcnt(0)
	s_barrier
	s_setprio 1
	v_mfma_f32_16x16x32_bf16 v[64:67], v[146:149], v[196:199], v[64:67]
	v_mfma_f32_16x16x32_bf16 v[64:67], v[150:153], v[200:203], v[64:67]
	v_mfma_f32_16x16x32_bf16 v[60:63], v[176:179], v[200:203], v[60:63]
	v_mfma_f32_16x16x32_bf16 v[60:63], v[172:175], v[196:199], v[60:63]
	v_mfma_f32_16x16x32_bf16 v[44:47], v[172:175], v[204:207], v[44:47]
	v_mfma_f32_16x16x32_bf16 v[44:47], v[176:179], v[208:211], v[44:47]
	v_mfma_f32_16x16x32_bf16 v[48:51], v[150:153], v[208:211], v[48:51]
	v_mfma_f32_16x16x32_bf16 v[48:51], v[146:149], v[204:207], v[48:51]
	v_mfma_f32_16x16x32_bf16 v[32:35], v[146:149], v[212:215], v[32:35]
	v_mfma_f32_16x16x32_bf16 v[32:35], v[150:153], v[216:219], v[32:35]
	v_mfma_f32_16x16x32_bf16 v[28:31], v[176:179], v[216:219], v[28:31]
	v_mfma_f32_16x16x32_bf16 v[28:31], v[172:175], v[212:215], v[28:31]
	v_mfma_f32_16x16x32_bf16 v[12:15], v[172:175], v[228:231], v[12:15]
	v_mfma_f32_16x16x32_bf16 v[12:15], v[176:179], v[232:235], v[12:15]
	v_mfma_f32_16x16x32_bf16 v[16:19], v[150:153], v[232:235], v[16:19]
	v_mfma_f32_16x16x32_bf16 v[16:19], v[146:149], v[228:231], v[16:19]
	v_mfma_f32_16x16x32_bf16 v[56:59], v[180:183], v[196:199], v[56:59]
	v_mfma_f32_16x16x32_bf16 v[56:59], v[184:187], v[200:203], v[56:59]
	v_mfma_f32_16x16x32_bf16 v[52:55], v[192:195], v[200:203], v[52:55]
	v_mfma_f32_16x16x32_bf16 v[52:55], v[188:191], v[196:199], v[52:55]
	v_mfma_f32_16x16x32_bf16 v[36:39], v[188:191], v[204:207], v[36:39]
	v_mfma_f32_16x16x32_bf16 v[36:39], v[192:195], v[208:211], v[36:39]
	v_mfma_f32_16x16x32_bf16 v[40:43], v[184:187], v[208:211], v[40:43]
	v_mfma_f32_16x16x32_bf16 v[40:43], v[180:183], v[204:207], v[40:43]
	v_mfma_f32_16x16x32_bf16 v[24:27], v[180:183], v[212:215], v[24:27]
	v_mfma_f32_16x16x32_bf16 v[24:27], v[184:187], v[216:219], v[24:27]
	v_mfma_f32_16x16x32_bf16 v[20:23], v[192:195], v[216:219], v[20:23]
	v_mfma_f32_16x16x32_bf16 v[20:23], v[188:191], v[212:215], v[20:23]
	v_mfma_f32_16x16x32_bf16 v[4:7], v[188:191], v[228:231], v[4:7]
	v_mfma_f32_16x16x32_bf16 v[4:7], v[192:195], v[232:235], v[4:7]
	v_mfma_f32_16x16x32_bf16 v[8:11], v[184:187], v[232:235], v[8:11]
	v_mfma_f32_16x16x32_bf16 v[8:11], v[180:183], v[228:231], v[8:11]
	s_setprio 0
	s_barrier
	s_add_i32 s77, s77, 2
	s_add_u32 s71, s71, 0x2c0000
	s_addc_u32 s76, s76, 0
	s_add_u32 s50, s50, 0x100
	s_addc_u32 s51, s51, 0
	s_cmp_gt_u32 s77, 29
	s_cbranch_scc0 .LBB0_169
	s_and_b64 vcc, exec, s[28:29]
	s_cbranch_vccz .LBB0_172
	s_barrier

.LBB0_243:
	s_add_u32 s34, s44, 0xfff80080
	s_addc_u32 s35, s45, -1
	s_add_i32 s52, 0, 0x10000
	s_cmp_eq_u32 vcc_hi, 28
	s_cselect_b32 s47, s36, s35
	s_cselect_b32 s46, s37, s34
	s_cselect_b32 s35, s55, vcc_lo
	s_cselect_b32 s34, s57, s63
	s_add_i32 s68, 0, 0x14000
	v_add_u32_e32 v144, s52, v155
	v_add_u32_e32 v180, s68, v155
	ds_read_b128 v[132:135], v144
	ds_read_b128 v[136:139], v144 offset:1024
	ds_read_b128 v[140:143], v144 offset:2048
	ds_read_b128 v[144:147], v144 offset:3072
	ds_read_b128 v[176:179], v180
	ds_read_b128 v[182:185], v180 offset:1024
	ds_read_b128 v[186:189], v180 offset:2048
	ds_read_b128 v[190:193], v180 offset:3072
	v_lshl_add_u64 v[218:219], s[44:45], 0, v[172:173]
	s_add_i32 m0, s69, 0xc000
	ds_read_b128 v[194:197], v181
	ds_read_b128 v[198:201], v181 offset:1024
	ds_read_b128 v[202:205], v181 offset:2048
	ds_read_b128 v[206:209], v181 offset:3072
	ds_read_b128 v[210:213], v181 offset:4096
	ds_read_b128 v[214:217], v181 offset:5120
	ds_read_b128 v[228:231], v181 offset:6144
	ds_read_b128 v[232:235], v181 offset:7168
	global_load_lds_dwordx4 v[218:219], off
	v_lshl_add_u64 v[218:219], s[44:45], 0, v[174:175]
	s_add_i32 m0, s69, 0xe000
	s_nop 0
	global_load_lds_dwordx4 v[218:219], off
	s_waitcnt vmcnt(8)
	s_waitcnt lgkmcnt(0)
	s_barrier
	s_setprio 1
	v_mfma_f32_16x16x32_bf16 v[128:131], v[132:135], v[194:197], v[128:131]
	v_mfma_f32_16x16x32_bf16 v[128:131], v[136:139], v[198:201], v[128:131]
	v_mfma_f32_16x16x32_bf16 v[124:127], v[144:147], v[198:201], v[124:127]
	v_mfma_f32_16x16x32_bf16 v[124:127], v[140:143], v[194:197], v[124:127]
	v_mfma_f32_16x16x32_bf16 v[108:111], v[140:143], v[202:205], v[108:111]
	v_mfma_f32_16x16x32_bf16 v[108:111], v[144:147], v[206:209], v[108:111]
	v_mfma_f32_16x16x32_bf16 v[112:115], v[136:139], v[206:209], v[112:115]
	v_mfma_f32_16x16x32_bf16 v[112:115], v[132:135], v[202:205], v[112:115]
	v_mfma_f32_16x16x32_bf16 v[96:99], v[132:135], v[210:213], v[96:99]
	v_mfma_f32_16x16x32_bf16 v[96:99], v[136:139], v[214:217], v[96:99]
	v_mfma_f32_16x16x32_bf16 v[92:95], v[144:147], v[214:217], v[92:95]
	v_mfma_f32_16x16x32_bf16 v[92:95], v[140:143], v[210:213], v[92:95]
	v_mfma_f32_16x16x32_bf16 v[76:79], v[140:143], v[228:231], v[76:79]
	v_mfma_f32_16x16x32_bf16 v[76:79], v[144:147], v[232:235], v[76:79]
	v_mfma_f32_16x16x32_bf16 v[80:83], v[136:139], v[232:235], v[80:83]
	v_mfma_f32_16x16x32_bf16 v[80:83], v[132:135], v[228:231], v[80:83]
	v_mfma_f32_16x16x32_bf16 v[120:123], v[176:179], v[194:197], v[120:123]
	v_mfma_f32_16x16x32_bf16 v[120:123], v[182:185], v[198:201], v[120:123]
	v_mfma_f32_16x16x32_bf16 v[116:119], v[190:193], v[198:201], v[116:119]
	v_mfma_f32_16x16x32_bf16 v[116:119], v[186:189], v[194:197], v[116:119]
	v_mfma_f32_16x16x32_bf16 v[100:103], v[186:189], v[202:205], v[100:103]
	v_mfma_f32_16x16x32_bf16 v[100:103], v[190:193], v[206:209], v[100:103]
	v_mfma_f32_16x16x32_bf16 v[104:107], v[182:185], v[206:209], v[104:107]
	v_mfma_f32_16x16x32_bf16 v[104:107], v[176:179], v[202:205], v[104:107]
	v_mfma_f32_16x16x32_bf16 v[88:91], v[176:179], v[210:213], v[88:91]
	v_mfma_f32_16x16x32_bf16 v[88:91], v[182:185], v[214:217], v[88:91]
	v_mfma_f32_16x16x32_bf16 v[84:87], v[190:193], v[214:217], v[84:87]
	v_mfma_f32_16x16x32_bf16 v[84:87], v[186:189], v[210:213], v[84:87]
	v_mfma_f32_16x16x32_bf16 v[68:71], v[186:189], v[228:231], v[68:71]
	v_mfma_f32_16x16x32_bf16 v[68:71], v[190:193], v[232:235], v[68:71]
	v_mfma_f32_16x16x32_bf16 v[72:75], v[182:185], v[232:235], v[72:75]
	v_mfma_f32_16x16x32_bf16 v[72:75], v[176:179], v[228:231], v[72:75]
	s_setprio 0
	s_barrier
	s_add_i32 s52, s52, s2
	v_lshl_add_u64 v[218:219], s[34:35], 0, v[150:151]
	s_mov_b32 m0, s52
	ds_read_b128 v[194:197], v181 offset:16384
	ds_read_b128 v[198:201], v181 offset:17408
	ds_read_b128 v[202:205], v181 offset:18432
	ds_read_b128 v[206:209], v181 offset:19456
	ds_read_b128 v[210:213], v181 offset:20480
	ds_read_b128 v[214:217], v181 offset:21504
	ds_read_b128 v[228:231], v181 offset:22528
	ds_read_b128 v[232:235], v181 offset:23552
	global_load_lds_dwordx4 v[218:219], off
	s_add_i32 m0, s52, 0x2000
	s_add_u32 s52, s34, 0x4000
	v_lshl_add_u64 v[218:219], s[34:35], 0, v[0:1]
	s_addc_u32 s53, s35, 0
	s_add_i32 s68, s68, s2
	global_load_lds_dwordx4 v[218:219], off
	v_lshl_add_u64 v[218:219], s[52:53], 0, v[150:151]
	s_mov_b32 m0, s68
	v_lshl_add_u64 v[236:237], s[46:47], 0, v[148:149]
	global_load_lds_dwordx4 v[218:219], off
	v_lshl_add_u64 v[218:219], s[52:53], 0, v[0:1]
	s_add_i32 m0, s68, 0x2000
	s_nop 0
	global_load_lds_dwordx4 v[218:219], off
	v_lshl_add_u64 v[218:219], s[46:47], 0, v[152:153]
	s_mov_b32 m0, s69
	s_nop 0
	global_load_lds_dwordx4 v[218:219], off
	s_mov_b32 m0, s71
	s_nop 0
	global_load_lds_dwordx4 v[236:237], off
	s_waitcnt vmcnt(8)
	s_waitcnt lgkmcnt(0)
	s_barrier
	s_setprio 1
	v_mfma_f32_16x16x32_bf16 v[64:67], v[132:135], v[194:197], v[64:67]
	v_mfma_f32_16x16x32_bf16 v[64:67], v[136:139], v[198:201], v[64:67]
	v_mfma_f32_16x16x32_bf16 v[60:63], v[144:147], v[198:201], v[60:63]
	v_mfma_f32_16x16x32_bf16 v[60:63], v[140:143], v[194:197], v[60:63]
	v_mfma_f32_16x16x32_bf16 v[44:47], v[140:143], v[202:205], v[44:47]
	v_mfma_f32_16x16x32_bf16 v[44:47], v[144:147], v[206:209], v[44:47]
	v_mfma_f32_16x16x32_bf16 v[48:51], v[136:139], v[206:209], v[48:51]
	v_mfma_f32_16x16x32_bf16 v[48:51], v[132:135], v[202:205], v[48:51]
	v_mfma_f32_16x16x32_bf16 v[32:35], v[132:135], v[210:213], v[32:35]
	v_mfma_f32_16x16x32_bf16 v[32:35], v[136:139], v[214:217], v[32:35]
	v_mfma_f32_16x16x32_bf16 v[28:31], v[144:147], v[214:217], v[28:31]
	v_mfma_f32_16x16x32_bf16 v[28:31], v[140:143], v[210:213], v[28:31]
	v_mfma_f32_16x16x32_bf16 v[12:15], v[140:143], v[228:231], v[12:15]
	v_mfma_f32_16x16x32_bf16 v[12:15], v[144:147], v[232:235], v[12:15]
	v_mfma_f32_16x16x32_bf16 v[16:19], v[136:139], v[232:235], v[16:19]
	v_mfma_f32_16x16x32_bf16 v[16:19], v[132:135], v[228:231], v[16:19]
	v_mfma_f32_16x16x32_bf16 v[56:59], v[176:179], v[194:197], v[56:59]
	v_mfma_f32_16x16x32_bf16 v[56:59], v[182:185], v[198:201], v[56:59]
	v_mfma_f32_16x16x32_bf16 v[52:55], v[190:193], v[198:201], v[52:55]
	v_mfma_f32_16x16x32_bf16 v[52:55], v[186:189], v[194:197], v[52:55]
	v_mfma_f32_16x16x32_bf16 v[36:39], v[186:189], v[202:205], v[36:39]
	v_mfma_f32_16x16x32_bf16 v[36:39], v[190:193], v[206:209], v[36:39]
	v_mfma_f32_16x16x32_bf16 v[40:43], v[182:185], v[206:209], v[40:43]
	v_mfma_f32_16x16x32_bf16 v[40:43], v[176:179], v[202:205], v[40:43]
	v_mfma_f32_16x16x32_bf16 v[24:27], v[176:179], v[210:213], v[24:27]
	v_mfma_f32_16x16x32_bf16 v[24:27], v[182:185], v[214:217], v[24:27]
	v_mfma_f32_16x16x32_bf16 v[20:23], v[190:193], v[214:217], v[20:23]
	v_mfma_f32_16x16x32_bf16 v[20:23], v[186:189], v[210:213], v[20:23]
	v_mfma_f32_16x16x32_bf16 v[4:7], v[186:189], v[228:231], v[4:7]
	v_mfma_f32_16x16x32_bf16 v[4:7], v[190:193], v[232:235], v[4:7]
	v_mfma_f32_16x16x32_bf16 v[8:11], v[182:185], v[232:235], v[8:11]
	v_mfma_f32_16x16x32_bf16 v[8:11], v[176:179], v[228:231], v[8:11]
	s_setprio 0
	s_barrier
	s_add_i32 s52, 0, 0x18000
	s_add_i32 s53, 0, 0x1c000
	v_add_u32_e32 v144, s52, v155
	v_add_u32_e32 v180, s53, v155
	ds_read_b128 v[132:135], v144
	ds_read_b128 v[136:139], v144 offset:1024
	ds_read_b128 v[140:143], v144 offset:2048
	ds_read_b128 v[144:147], v144 offset:3072
	ds_read_b128 v[176:179], v180
	ds_read_b128 v[182:185], v180 offset:1024
	ds_read_b128 v[186:189], v180 offset:2048
	ds_read_b128 v[190:193], v180 offset:3072
	s_add_u32 s46, s46, 0x80000
	s_addc_u32 s47, s47, 0
	s_mov_b32 m0, s88
	v_lshl_add_u64 v[238:239], s[46:47], 0, v[152:153]
	ds_read_b128 v[194:197], v181 offset:32768
	ds_read_b128 v[198:201], v181 offset:33792
	ds_read_b128 v[202:205], v181 offset:34816
	ds_read_b128 v[206:209], v181 offset:35840
	ds_read_b128 v[210:213], v181 offset:36864
	ds_read_b128 v[214:217], v181 offset:37888
	ds_read_b128 v[228:231], v181 offset:38912
	ds_read_b128 v[232:235], v181 offset:39936
	global_load_lds_dwordx4 v[238:239], off
	v_lshl_add_u64 v[238:239], s[46:47], 0, v[148:149]
	s_mov_b32 m0, s96
	s_nop 0
	global_load_lds_dwordx4 v[238:239], off
	s_waitcnt vmcnt(8)
	s_waitcnt lgkmcnt(0)
	s_barrier
	s_setprio 1
	v_mfma_f32_16x16x32_bf16 v[128:131], v[132:135], v[194:197], v[128:131]
	v_mfma_f32_16x16x32_bf16 v[128:131], v[136:139], v[198:201], v[128:131]
	v_mfma_f32_16x16x32_bf16 v[124:127], v[144:147], v[198:201], v[124:127]
	v_mfma_f32_16x16x32_bf16 v[124:127], v[140:143], v[194:197], v[124:127]
	v_mfma_f32_16x16x32_bf16 v[108:111], v[140:143], v[202:205], v[108:111]
	v_mfma_f32_16x16x32_bf16 v[108:111], v[144:147], v[206:209], v[108:111]
	v_mfma_f32_16x16x32_bf16 v[112:115], v[136:139], v[206:209], v[112:115]
	v_mfma_f32_16x16x32_bf16 v[112:115], v[132:135], v[202:205], v[112:115]
	v_mfma_f32_16x16x32_bf16 v[96:99], v[132:135], v[210:213], v[96:99]
	v_mfma_f32_16x16x32_bf16 v[96:99], v[136:139], v[214:217], v[96:99]
	v_mfma_f32_16x16x32_bf16 v[92:95], v[144:147], v[214:217], v[92:95]
	v_mfma_f32_16x16x32_bf16 v[92:95], v[140:143], v[210:213], v[92:95]
	v_mfma_f32_16x16x32_bf16 v[76:79], v[140:143], v[228:231], v[76:79]
	v_mfma_f32_16x16x32_bf16 v[76:79], v[144:147], v[232:235], v[76:79]
	v_mfma_f32_16x16x32_bf16 v[80:83], v[136:139], v[232:235], v[80:83]
	v_mfma_f32_16x16x32_bf16 v[80:83], v[132:135], v[228:231], v[80:83]
	v_mfma_f32_16x16x32_bf16 v[120:123], v[176:179], v[194:197], v[120:123]
	v_mfma_f32_16x16x32_bf16 v[120:123], v[182:185], v[198:201], v[120:123]
	v_mfma_f32_16x16x32_bf16 v[116:119], v[190:193], v[198:201], v[116:119]
	v_mfma_f32_16x16x32_bf16 v[116:119], v[186:189], v[194:197], v[116:119]
	v_mfma_f32_16x16x32_bf16 v[100:103], v[186:189], v[202:205], v[100:103]
	v_mfma_f32_16x16x32_bf16 v[100:103], v[190:193], v[206:209], v[100:103]
	v_mfma_f32_16x16x32_bf16 v[104:107], v[182:185], v[206:209], v[104:107]
	v_mfma_f32_16x16x32_bf16 v[104:107], v[176:179], v[202:205], v[104:107]
	v_mfma_f32_16x16x32_bf16 v[88:91], v[176:179], v[210:213], v[88:91]
	v_mfma_f32_16x16x32_bf16 v[88:91], v[182:185], v[214:217], v[88:91]
	v_mfma_f32_16x16x32_bf16 v[84:87], v[190:193], v[214:217], v[84:87]
	v_mfma_f32_16x16x32_bf16 v[84:87], v[186:189], v[210:213], v[84:87]
	v_mfma_f32_16x16x32_bf16 v[68:71], v[186:189], v[228:231], v[68:71]
	v_mfma_f32_16x16x32_bf16 v[68:71], v[190:193], v[232:235], v[68:71]
	v_mfma_f32_16x16x32_bf16 v[72:75], v[182:185], v[232:235], v[72:75]
	v_mfma_f32_16x16x32_bf16 v[72:75], v[176:179], v[228:231], v[72:75]
	s_setprio 0
	s_barrier
	s_add_u32 s46, s34, 0x70000
	s_addc_u32 s47, s35, 0
	s_add_i32 s52, s52, s2
	v_lshl_add_u64 v[238:239], s[46:47], 0, v[150:151]
	s_mov_b32 m0, s52
	ds_read_b128 v[194:197], v181 offset:49152
	ds_read_b128 v[198:201], v181 offset:50176
	ds_read_b128 v[202:205], v181 offset:51200
	ds_read_b128 v[206:209], v181 offset:52224
	ds_read_b128 v[210:213], v181 offset:53248
	ds_read_b128 v[214:217], v181 offset:54272
	ds_read_b128 v[228:231], v181 offset:55296
	ds_read_b128 v[232:235], v181 offset:56320
	global_load_lds_dwordx4 v[238:239], off
	s_add_i32 m0, s52, 0x2000
	s_add_u32 s34, s34, 0x74000
	v_lshl_add_u64 v[238:239], s[46:47], 0, v[0:1]
	s_addc_u32 s35, s35, 0
	s_add_i32 s46, s53, s2
	global_load_lds_dwordx4 v[238:239], off
	v_lshl_add_u64 v[238:239], s[34:35], 0, v[150:151]
	s_mov_b32 m0, s46
	v_lshl_add_u64 v[218:219], v[218:219], 0, s[14:15]
	global_load_lds_dwordx4 v[238:239], off
	v_lshl_add_u64 v[238:239], s[34:35], 0, v[0:1]
	s_add_i32 m0, s46, 0x2000
	s_nop 0
	global_load_lds_dwordx4 v[238:239], off
	s_mov_b32 m0, s97
	s_nop 0
	global_load_lds_dwordx4 v[218:219], off
	v_lshl_add_u64 v[218:219], v[236:237], 0, s[14:15]
	s_mov_b32 m0, s76
	s_nop 0
	global_load_lds_dwordx4 v[218:219], off
	s_waitcnt vmcnt(8)
	s_waitcnt lgkmcnt(0)
	s_barrier
	s_setprio 1
	v_mfma_f32_16x16x32_bf16 v[64:67], v[132:135], v[194:197], v[64:67]
	v_mfma_f32_16x16x32_bf16 v[64:67], v[136:139], v[198:201], v[64:67]
	v_mfma_f32_16x16x32_bf16 v[60:63], v[144:147], v[198:201], v[60:63]
	v_mfma_f32_16x16x32_bf16 v[60:63], v[140:143], v[194:197], v[60:63]
	v_mfma_f32_16x16x32_bf16 v[44:47], v[140:143], v[202:205], v[44:47]
	v_mfma_f32_16x16x32_bf16 v[44:47], v[144:147], v[206:209], v[44:47]
	v_mfma_f32_16x16x32_bf16 v[48:51], v[136:139], v[206:209], v[48:51]
	v_mfma_f32_16x16x32_bf16 v[48:51], v[132:135], v[202:205], v[48:51]
	v_mfma_f32_16x16x32_bf16 v[32:35], v[132:135], v[210:213], v[32:35]
	v_mfma_f32_16x16x32_bf16 v[32:35], v[136:139], v[214:217], v[32:35]
	v_mfma_f32_16x16x32_bf16 v[28:31], v[144:147], v[214:217], v[28:31]
	v_mfma_f32_16x16x32_bf16 v[28:31], v[140:143], v[210:213], v[28:31]
	v_mfma_f32_16x16x32_bf16 v[12:15], v[140:143], v[228:231], v[12:15]
	v_mfma_f32_16x16x32_bf16 v[12:15], v[144:147], v[232:235], v[12:15]
	v_mfma_f32_16x16x32_bf16 v[16:19], v[136:139], v[232:235], v[16:19]
	v_mfma_f32_16x16x32_bf16 v[16:19], v[132:135], v[228:231], v[16:19]
	v_mfma_f32_16x16x32_bf16 v[56:59], v[176:179], v[194:197], v[56:59]
	v_mfma_f32_16x16x32_bf16 v[56:59], v[182:185], v[198:201], v[56:59]
	v_mfma_f32_16x16x32_bf16 v[52:55], v[190:193], v[198:201], v[52:55]
	v_mfma_f32_16x16x32_bf16 v[52:55], v[186:189], v[194:197], v[52:55]
	v_mfma_f32_16x16x32_bf16 v[36:39], v[186:189], v[202:205], v[36:39]
	v_mfma_f32_16x16x32_bf16 v[36:39], v[190:193], v[206:209], v[36:39]
	v_mfma_f32_16x16x32_bf16 v[40:43], v[182:185], v[206:209], v[40:43]
	v_mfma_f32_16x16x32_bf16 v[40:43], v[176:179], v[202:205], v[40:43]
	v_mfma_f32_16x16x32_bf16 v[24:27], v[176:179], v[210:213], v[24:27]
	v_mfma_f32_16x16x32_bf16 v[24:27], v[182:185], v[214:217], v[24:27]
	v_mfma_f32_16x16x32_bf16 v[20:23], v[190:193], v[214:217], v[20:23]
	v_mfma_f32_16x16x32_bf16 v[20:23], v[186:189], v[210:213], v[20:23]
	v_mfma_f32_16x16x32_bf16 v[4:7], v[186:189], v[228:231], v[4:7]
	v_mfma_f32_16x16x32_bf16 v[4:7], v[190:193], v[232:235], v[4:7]
	v_mfma_f32_16x16x32_bf16 v[8:11], v[182:185], v[232:235], v[8:11]
	v_mfma_f32_16x16x32_bf16 v[8:11], v[176:179], v[228:231], v[8:11]
	s_setprio 0
	s_barrier
	s_add_i32 vcc_hi, vcc_hi, 2
	s_add_u32 s63, s63, 0xe0000
	s_addc_u32 vcc_lo, vcc_lo, 0
	s_add_u32 s44, s44, 0x100
	s_addc_u32 s45, s45, 0
	s_cmp_gt_u32 vcc_hi, 29
	s_cbranch_scc0 .LBB0_243
	s_and_b64 vcc, exec, s[28:29]
	s_cbranch_vccz .LBB0_246
	s_barrier

.LBB0_559:
	s_add_i32 vcc_lo, s34, 2
	s_add_u32 s35, s42, 0x80
	s_addc_u32 s52, s43, 0
	s_add_i32 s53, 0, 0x10000
	s_cmp_eq_u32 s77, s34
	s_cselect_b32 s57, s51, s52
	s_cselect_b32 s56, s50, s35
	s_cselect_b32 s35, s36, s97
	s_cselect_b32 s34, s37, s49
	s_add_i32 s68, 0, 0x14000
	v_add_u32_e32 v136, s53, v200
	v_add_u32_e32 v186, s68, v200
	ds_read_b128 v[116:119], v136
	ds_read_b128 v[120:123], v136 offset:1024
	ds_read_b128 v[124:127], v136 offset:2048
	ds_read_b128 v[136:139], v136 offset:3072
	ds_read_b128 v[148:151], v186
	ds_read_b128 v[152:155], v186 offset:1024
	ds_read_b128 v[182:185], v186 offset:2048
	ds_read_b128 v[186:189], v186 offset:3072
	v_lshl_add_u64 v[198:199], s[42:43], 0, v[178:179]
	s_add_i32 m0, s59, 0xc000
	ds_read_b128 v[190:193], v202
	ds_read_b128 v[194:197], v202 offset:1024
	ds_read_b128 v[204:207], v202 offset:2048
	ds_read_b128 v[208:211], v202 offset:3072
	ds_read_b128 v[212:215], v202 offset:4096
	ds_read_b128 v[216:219], v202 offset:5120
	ds_read_b128 v[228:231], v202 offset:6144
	ds_read_b128 v[232:235], v202 offset:7168
	global_load_lds_dwordx4 v[198:199], off
	v_lshl_add_u64 v[198:199], s[42:43], 0, v[180:181]
	s_add_i32 m0, s59, 0xe000
	s_nop 0
	global_load_lds_dwordx4 v[198:199], off
	s_waitcnt vmcnt(8)
	s_waitcnt lgkmcnt(0)
	s_barrier
	s_setprio 1
	v_mfma_f32_16x16x32_bf16 v[144:147], v[116:119], v[190:193], v[144:147]
	v_mfma_f32_16x16x32_bf16 v[144:147], v[120:123], v[194:197], v[144:147]
	v_mfma_f32_16x16x32_bf16 v[140:143], v[136:139], v[194:197], v[140:143]
	v_mfma_f32_16x16x32_bf16 v[140:143], v[124:127], v[190:193], v[140:143]
	v_mfma_f32_16x16x32_bf16 v[108:111], v[124:127], v[204:207], v[108:111]
	v_mfma_f32_16x16x32_bf16 v[108:111], v[136:139], v[208:211], v[108:111]
	v_mfma_f32_16x16x32_bf16 v[112:115], v[120:123], v[208:211], v[112:115]
	v_mfma_f32_16x16x32_bf16 v[112:115], v[116:119], v[204:207], v[112:115]
	v_mfma_f32_16x16x32_bf16 v[96:99], v[116:119], v[212:215], v[96:99]
	v_mfma_f32_16x16x32_bf16 v[96:99], v[120:123], v[216:219], v[96:99]
	v_mfma_f32_16x16x32_bf16 v[92:95], v[136:139], v[216:219], v[92:95]
	v_mfma_f32_16x16x32_bf16 v[92:95], v[124:127], v[212:215], v[92:95]
	v_mfma_f32_16x16x32_bf16 v[76:79], v[124:127], v[228:231], v[76:79]
	v_mfma_f32_16x16x32_bf16 v[76:79], v[136:139], v[232:235], v[76:79]
	v_mfma_f32_16x16x32_bf16 v[80:83], v[120:123], v[232:235], v[80:83]
	v_mfma_f32_16x16x32_bf16 v[80:83], v[116:119], v[228:231], v[80:83]
	v_mfma_f32_16x16x32_bf16 v[132:135], v[148:151], v[190:193], v[132:135]
	v_mfma_f32_16x16x32_bf16 v[132:135], v[152:155], v[194:197], v[132:135]
	v_mfma_f32_16x16x32_bf16 v[128:131], v[186:189], v[194:197], v[128:131]
	v_mfma_f32_16x16x32_bf16 v[128:131], v[182:185], v[190:193], v[128:131]
	v_mfma_f32_16x16x32_bf16 v[100:103], v[182:185], v[204:207], v[100:103]
	v_mfma_f32_16x16x32_bf16 v[100:103], v[186:189], v[208:211], v[100:103]
	v_mfma_f32_16x16x32_bf16 v[104:107], v[152:155], v[208:211], v[104:107]
	v_mfma_f32_16x16x32_bf16 v[104:107], v[148:151], v[204:207], v[104:107]
	v_mfma_f32_16x16x32_bf16 v[88:91], v[148:151], v[212:215], v[88:91]
	v_mfma_f32_16x16x32_bf16 v[88:91], v[152:155], v[216:219], v[88:91]
	v_mfma_f32_16x16x32_bf16 v[84:87], v[186:189], v[216:219], v[84:87]
	v_mfma_f32_16x16x32_bf16 v[84:87], v[182:185], v[212:215], v[84:87]
	v_mfma_f32_16x16x32_bf16 v[68:71], v[182:185], v[228:231], v[68:71]
	v_mfma_f32_16x16x32_bf16 v[68:71], v[186:189], v[232:235], v[68:71]
	v_mfma_f32_16x16x32_bf16 v[72:75], v[152:155], v[232:235], v[72:75]
	v_mfma_f32_16x16x32_bf16 v[72:75], v[148:151], v[228:231], v[72:75]
	s_setprio 0
	s_barrier
	s_add_i32 s52, s53, s58
	v_lshl_add_u64 v[198:199], s[34:35], 0, v[174:175]
	s_mov_b32 m0, s52
	ds_read_b128 v[190:193], v202 offset:16384
	ds_read_b128 v[194:197], v202 offset:17408
	ds_read_b128 v[204:207], v202 offset:18432
	ds_read_b128 v[208:211], v202 offset:19456
	ds_read_b128 v[212:215], v202 offset:20480
	ds_read_b128 v[216:219], v202 offset:21504
	ds_read_b128 v[228:231], v202 offset:22528
	ds_read_b128 v[232:235], v202 offset:23552
	global_load_lds_dwordx4 v[198:199], off
	s_add_i32 m0, s52, 0x2000
	s_add_u32 s52, s34, 0x4000
	v_lshl_add_u64 v[198:199], s[34:35], 0, v[0:1]
	s_addc_u32 s53, s35, 0
	s_add_i32 s68, s68, s58
	global_load_lds_dwordx4 v[198:199], off
	v_lshl_add_u64 v[198:199], s[52:53], 0, v[174:175]
	s_mov_b32 m0, s68
	v_lshl_add_u64 v[236:237], s[56:57], 0, v[172:173]
	global_load_lds_dwordx4 v[198:199], off
	v_lshl_add_u64 v[198:199], s[52:53], 0, v[0:1]
	s_add_i32 m0, s68, 0x2000
	s_nop 0
	global_load_lds_dwordx4 v[198:199], off
	v_lshl_add_u64 v[198:199], s[56:57], 0, v[176:177]
	s_mov_b32 m0, s59
	s_nop 0
	global_load_lds_dwordx4 v[198:199], off
	s_mov_b32 m0, s60
	s_nop 0
	global_load_lds_dwordx4 v[236:237], off
	s_waitcnt vmcnt(8)
	s_waitcnt lgkmcnt(0)
	s_barrier
	s_setprio 1
	v_mfma_f32_16x16x32_bf16 v[64:67], v[116:119], v[190:193], v[64:67]
	v_mfma_f32_16x16x32_bf16 v[64:67], v[120:123], v[194:197], v[64:67]
	v_mfma_f32_16x16x32_bf16 v[60:63], v[136:139], v[194:197], v[60:63]
	v_mfma_f32_16x16x32_bf16 v[60:63], v[124:127], v[190:193], v[60:63]
	v_mfma_f32_16x16x32_bf16 v[44:47], v[124:127], v[204:207], v[44:47]
	v_mfma_f32_16x16x32_bf16 v[44:47], v[136:139], v[208:211], v[44:47]
	v_mfma_f32_16x16x32_bf16 v[48:51], v[120:123], v[208:211], v[48:51]
	v_mfma_f32_16x16x32_bf16 v[48:51], v[116:119], v[204:207], v[48:51]
	v_mfma_f32_16x16x32_bf16 v[32:35], v[116:119], v[212:215], v[32:35]
	v_mfma_f32_16x16x32_bf16 v[32:35], v[120:123], v[216:219], v[32:35]
	v_mfma_f32_16x16x32_bf16 v[28:31], v[136:139], v[216:219], v[28:31]
	v_mfma_f32_16x16x32_bf16 v[28:31], v[124:127], v[212:215], v[28:31]
	v_mfma_f32_16x16x32_bf16 v[12:15], v[124:127], v[228:231], v[12:15]
	v_mfma_f32_16x16x32_bf16 v[12:15], v[136:139], v[232:235], v[12:15]
	v_mfma_f32_16x16x32_bf16 v[16:19], v[120:123], v[232:235], v[16:19]
	v_mfma_f32_16x16x32_bf16 v[16:19], v[116:119], v[228:231], v[16:19]
	v_mfma_f32_16x16x32_bf16 v[56:59], v[148:151], v[190:193], v[56:59]
	v_mfma_f32_16x16x32_bf16 v[56:59], v[152:155], v[194:197], v[56:59]
	v_mfma_f32_16x16x32_bf16 v[52:55], v[186:189], v[194:197], v[52:55]
	v_mfma_f32_16x16x32_bf16 v[52:55], v[182:185], v[190:193], v[52:55]
	v_mfma_f32_16x16x32_bf16 v[36:39], v[182:185], v[204:207], v[36:39]
	v_mfma_f32_16x16x32_bf16 v[36:39], v[186:189], v[208:211], v[36:39]
	v_mfma_f32_16x16x32_bf16 v[40:43], v[152:155], v[208:211], v[40:43]
	v_mfma_f32_16x16x32_bf16 v[40:43], v[148:151], v[204:207], v[40:43]
	v_mfma_f32_16x16x32_bf16 v[24:27], v[148:151], v[212:215], v[24:27]
	v_mfma_f32_16x16x32_bf16 v[24:27], v[152:155], v[216:219], v[24:27]
	v_mfma_f32_16x16x32_bf16 v[20:23], v[186:189], v[216:219], v[20:23]
	v_mfma_f32_16x16x32_bf16 v[20:23], v[182:185], v[212:215], v[20:23]
	v_mfma_f32_16x16x32_bf16 v[4:7], v[182:185], v[228:231], v[4:7]
	v_mfma_f32_16x16x32_bf16 v[4:7], v[186:189], v[232:235], v[4:7]
	v_mfma_f32_16x16x32_bf16 v[8:11], v[152:155], v[232:235], v[8:11]
	v_mfma_f32_16x16x32_bf16 v[8:11], v[148:151], v[228:231], v[8:11]
	s_setprio 0
	s_barrier
	s_add_i32 s68, 0, 0x18000
	s_add_i32 vcc_hi, 0, 0x1c000
	v_add_u32_e32 v136, s68, v200
	v_add_u32_e32 v186, vcc_hi, v200
	ds_read_b128 v[116:119], v136
	ds_read_b128 v[120:123], v136 offset:1024
	ds_read_b128 v[124:127], v136 offset:2048
	ds_read_b128 v[136:139], v136 offset:3072
	ds_read_b128 v[148:151], v186
	ds_read_b128 v[152:155], v186 offset:1024
	ds_read_b128 v[182:185], v186 offset:2048
	ds_read_b128 v[186:189], v186 offset:3072
	s_add_u32 s52, s56, s26
	s_addc_u32 s53, s57, 0
	s_mov_b32 m0, s61
	v_lshl_add_u64 v[238:239], s[52:53], 0, v[176:177]
	ds_read_b128 v[190:193], v202 offset:32768
	ds_read_b128 v[194:197], v202 offset:33792
	ds_read_b128 v[204:207], v202 offset:34816
	ds_read_b128 v[208:211], v202 offset:35840
	ds_read_b128 v[212:215], v202 offset:36864
	ds_read_b128 v[216:219], v202 offset:37888
	ds_read_b128 v[228:231], v202 offset:38912
	ds_read_b128 v[232:235], v202 offset:39936
	global_load_lds_dwordx4 v[238:239], off
	v_lshl_add_u64 v[238:239], s[52:53], 0, v[172:173]
	s_mov_b32 m0, s62
	s_nop 0
	global_load_lds_dwordx4 v[238:239], off
	s_waitcnt vmcnt(8)
	s_waitcnt lgkmcnt(0)
	s_barrier
	s_setprio 1
	v_mfma_f32_16x16x32_bf16 v[144:147], v[116:119], v[190:193], v[144:147]
	v_mfma_f32_16x16x32_bf16 v[144:147], v[120:123], v[194:197], v[144:147]
	v_mfma_f32_16x16x32_bf16 v[140:143], v[136:139], v[194:197], v[140:143]
	v_mfma_f32_16x16x32_bf16 v[140:143], v[124:127], v[190:193], v[140:143]
	v_mfma_f32_16x16x32_bf16 v[108:111], v[124:127], v[204:207], v[108:111]
	v_mfma_f32_16x16x32_bf16 v[108:111], v[136:139], v[208:211], v[108:111]
	v_mfma_f32_16x16x32_bf16 v[112:115], v[120:123], v[208:211], v[112:115]
	v_mfma_f32_16x16x32_bf16 v[112:115], v[116:119], v[204:207], v[112:115]
	v_mfma_f32_16x16x32_bf16 v[96:99], v[116:119], v[212:215], v[96:99]
	v_mfma_f32_16x16x32_bf16 v[96:99], v[120:123], v[216:219], v[96:99]
	v_mfma_f32_16x16x32_bf16 v[92:95], v[136:139], v[216:219], v[92:95]
	v_mfma_f32_16x16x32_bf16 v[92:95], v[124:127], v[212:215], v[92:95]
	v_mfma_f32_16x16x32_bf16 v[76:79], v[124:127], v[228:231], v[76:79]
	v_mfma_f32_16x16x32_bf16 v[76:79], v[136:139], v[232:235], v[76:79]
	v_mfma_f32_16x16x32_bf16 v[80:83], v[120:123], v[232:235], v[80:83]
	v_mfma_f32_16x16x32_bf16 v[80:83], v[116:119], v[228:231], v[80:83]
	v_mfma_f32_16x16x32_bf16 v[132:135], v[148:151], v[190:193], v[132:135]
	v_mfma_f32_16x16x32_bf16 v[132:135], v[152:155], v[194:197], v[132:135]
	v_mfma_f32_16x16x32_bf16 v[128:131], v[186:189], v[194:197], v[128:131]
	v_mfma_f32_16x16x32_bf16 v[128:131], v[182:185], v[190:193], v[128:131]
	v_mfma_f32_16x16x32_bf16 v[100:103], v[182:185], v[204:207], v[100:103]
	v_mfma_f32_16x16x32_bf16 v[100:103], v[186:189], v[208:211], v[100:103]
	v_mfma_f32_16x16x32_bf16 v[104:107], v[152:155], v[208:211], v[104:107]
	v_mfma_f32_16x16x32_bf16 v[104:107], v[148:151], v[204:207], v[104:107]
	v_mfma_f32_16x16x32_bf16 v[88:91], v[148:151], v[212:215], v[88:91]
	v_mfma_f32_16x16x32_bf16 v[88:91], v[152:155], v[216:219], v[88:91]
	v_mfma_f32_16x16x32_bf16 v[84:87], v[186:189], v[216:219], v[84:87]
	v_mfma_f32_16x16x32_bf16 v[84:87], v[182:185], v[212:215], v[84:87]
	v_mfma_f32_16x16x32_bf16 v[68:71], v[182:185], v[228:231], v[68:71]
	v_mfma_f32_16x16x32_bf16 v[68:71], v[186:189], v[232:235], v[68:71]
	v_mfma_f32_16x16x32_bf16 v[72:75], v[152:155], v[232:235], v[72:75]
	v_mfma_f32_16x16x32_bf16 v[72:75], v[148:151], v[228:231], v[72:75]
	s_setprio 0
	s_barrier
	s_add_u32 s52, s34, 0x40000
	s_addc_u32 s53, s35, 0
	s_add_i32 s56, s68, s58
	v_lshl_add_u64 v[238:239], s[52:53], 0, v[174:175]
	s_mov_b32 m0, s56
	ds_read_b128 v[190:193], v202 offset:49152
	ds_read_b128 v[194:197], v202 offset:50176
	ds_read_b128 v[204:207], v202 offset:51200
	ds_read_b128 v[208:211], v202 offset:52224
	ds_read_b128 v[212:215], v202 offset:53248
	ds_read_b128 v[216:219], v202 offset:54272
	ds_read_b128 v[228:231], v202 offset:55296
	ds_read_b128 v[232:235], v202 offset:56320
	global_load_lds_dwordx4 v[238:239], off
	s_add_i32 m0, s56, 0x2000
	s_add_u32 s34, s34, 0x44000
	v_lshl_add_u64 v[238:239], s[52:53], 0, v[0:1]
	s_addc_u32 s35, s35, 0
	s_add_i32 s52, vcc_hi, s58
	global_load_lds_dwordx4 v[238:239], off
	v_lshl_add_u64 v[238:239], s[34:35], 0, v[174:175]
	s_mov_b32 m0, s52
	v_lshl_add_u64 v[198:199], v[198:199], 0, s[14:15]
	global_load_lds_dwordx4 v[238:239], off
	v_lshl_add_u64 v[238:239], s[34:35], 0, v[0:1]
	s_add_i32 m0, s52, 0x2000
	s_nop 0
	global_load_lds_dwordx4 v[238:239], off
	s_mov_b32 m0, s71
	s_nop 0
	global_load_lds_dwordx4 v[198:199], off
	v_lshl_add_u64 v[198:199], v[236:237], 0, s[14:15]
	s_mov_b32 m0, s76
	s_nop 0
	global_load_lds_dwordx4 v[198:199], off
	s_waitcnt vmcnt(8)
	s_waitcnt lgkmcnt(0)
	s_barrier
	s_setprio 1
	v_mfma_f32_16x16x32_bf16 v[64:67], v[116:119], v[190:193], v[64:67]
	v_mfma_f32_16x16x32_bf16 v[64:67], v[120:123], v[194:197], v[64:67]
	v_mfma_f32_16x16x32_bf16 v[60:63], v[136:139], v[194:197], v[60:63]
	v_mfma_f32_16x16x32_bf16 v[60:63], v[124:127], v[190:193], v[60:63]
	v_mfma_f32_16x16x32_bf16 v[44:47], v[124:127], v[204:207], v[44:47]
	v_mfma_f32_16x16x32_bf16 v[44:47], v[136:139], v[208:211], v[44:47]
	v_mfma_f32_16x16x32_bf16 v[48:51], v[120:123], v[208:211], v[48:51]
	v_mfma_f32_16x16x32_bf16 v[48:51], v[116:119], v[204:207], v[48:51]
	v_mfma_f32_16x16x32_bf16 v[32:35], v[116:119], v[212:215], v[32:35]
	v_mfma_f32_16x16x32_bf16 v[32:35], v[120:123], v[216:219], v[32:35]
	v_mfma_f32_16x16x32_bf16 v[28:31], v[136:139], v[216:219], v[28:31]
	v_mfma_f32_16x16x32_bf16 v[28:31], v[124:127], v[212:215], v[28:31]
	v_mfma_f32_16x16x32_bf16 v[12:15], v[124:127], v[228:231], v[12:15]
	v_mfma_f32_16x16x32_bf16 v[12:15], v[136:139], v[232:235], v[12:15]
	v_mfma_f32_16x16x32_bf16 v[16:19], v[120:123], v[232:235], v[16:19]
	v_mfma_f32_16x16x32_bf16 v[16:19], v[116:119], v[228:231], v[16:19]
	v_mfma_f32_16x16x32_bf16 v[56:59], v[148:151], v[190:193], v[56:59]
	v_mfma_f32_16x16x32_bf16 v[56:59], v[152:155], v[194:197], v[56:59]
	v_mfma_f32_16x16x32_bf16 v[52:55], v[186:189], v[194:197], v[52:55]
	v_mfma_f32_16x16x32_bf16 v[52:55], v[182:185], v[190:193], v[52:55]
	v_mfma_f32_16x16x32_bf16 v[36:39], v[182:185], v[204:207], v[36:39]
	v_mfma_f32_16x16x32_bf16 v[36:39], v[186:189], v[208:211], v[36:39]
	v_mfma_f32_16x16x32_bf16 v[40:43], v[152:155], v[208:211], v[40:43]
	v_mfma_f32_16x16x32_bf16 v[40:43], v[148:151], v[204:207], v[40:43]
	v_mfma_f32_16x16x32_bf16 v[24:27], v[148:151], v[212:215], v[24:27]
	v_mfma_f32_16x16x32_bf16 v[24:27], v[152:155], v[216:219], v[24:27]
	v_mfma_f32_16x16x32_bf16 v[20:23], v[186:189], v[216:219], v[20:23]
	v_mfma_f32_16x16x32_bf16 v[20:23], v[182:185], v[212:215], v[20:23]
	v_mfma_f32_16x16x32_bf16 v[4:7], v[182:185], v[228:231], v[4:7]
	v_mfma_f32_16x16x32_bf16 v[4:7], v[186:189], v[232:235], v[4:7]
	v_mfma_f32_16x16x32_bf16 v[8:11], v[152:155], v[232:235], v[8:11]
	v_mfma_f32_16x16x32_bf16 v[8:11], v[148:151], v[228:231], v[8:11]
	s_setprio 0
	s_barrier
	s_add_u32 s49, s49, 0x80000
	s_addc_u32 s97, s97, 0
	s_add_u32 s42, s42, 0x100
	s_addc_u32 s43, s43, 0
	s_cmp_ge_u32 vcc_lo, s69
	s_mov_b32 s34, vcc_lo
	s_cbranch_scc0 .LBB0_559
	s_and_b64 vcc, exec, s[46:47]
	s_cbranch_vccz .LBB0_562
	s_barrier
